# v35 with all 16 residual-row touch loads issued together in phase 2 of the last k-iteration (vmcnt(16) at phase 4) so they have returned before the epilogue's first wait
# baseline (speedup 1.0000x reference)
.LBB0_1179:
	s_add_i32 s92, s42, 2
	s_add_u32 s72, s36, 0x80
	s_addc_u32 s43, s37, 0
	s_add_i32 s93, 0, 0x10000
	v_add_u32_e32 v1, s93, v223
	ds_read_b128 v[50:53], v1
	ds_read_b128 v[54:57], v1 offset:1024
	ds_read_b128 v[58:61], v1 offset:2048
	ds_read_b128 v[62:65], v1 offset:3072
	s_cmp_eq_u32 s88, s42
	s_cselect_b32 s42, s66, s72
	s_cselect_b32 s43, s67, s43
	s_cselect_b32 s73, s71, s91
	s_cselect_b32 s72, s70, s27
	v_lshl_add_u64 v[178:179], s[36:37], 0, v[206:207]
	s_add_i32 m0, s79, 0xc000
	ds_read_b128 v[66:69], v230
	ds_read_b128 v[70:73], v230 offset:1024
	ds_read_b128 v[74:77], v230 offset:2048
	ds_read_b128 v[78:81], v230 offset:3072
	ds_read_b128 v[146:149], v230 offset:4096
	ds_read_b128 v[154:157], v230 offset:5120
	ds_read_b128 v[170:173], v230 offset:6144
	ds_read_b128 v[174:177], v230 offset:7168
	global_load_lds_dwordx4 v[178:179], off
	v_lshl_add_u64 v[178:179], s[36:37], 0, v[204:205]
	s_add_i32 m0, s79, 0xe000
	s_nop 0
	global_load_lds_dwordx4 v[178:179], off
	s_waitcnt lgkmcnt(8)
	s_barrier
	s_waitcnt lgkmcnt(0)
	s_waitcnt lgkmcnt(0)
	v_mfma_f32_16x16x32_bf16 v[166:169], v[50:53], v[66:69], v[166:169]
	v_mfma_f32_16x16x32_bf16 v[162:165], v[58:61], v[66:69], v[162:165]
	v_mfma_f32_16x16x32_bf16 v[142:145], v[50:53], v[74:77], v[142:145]
	v_mfma_f32_16x16x32_bf16 v[138:141], v[58:61], v[74:77], v[138:141]
	v_mfma_f32_16x16x32_bf16 v[126:129], v[50:53], v[146:149], v[126:129]
	v_mfma_f32_16x16x32_bf16 v[122:125], v[58:61], v[146:149], v[122:125]
	v_mfma_f32_16x16x32_bf16 v[110:113], v[50:53], v[170:173], v[110:113]
	v_mfma_f32_16x16x32_bf16 v[106:109], v[58:61], v[170:173], v[106:109]
	v_mfma_f32_16x16x32_bf16 v[166:169], v[54:57], v[70:73], v[166:169]
	v_mfma_f32_16x16x32_bf16 v[162:165], v[62:65], v[70:73], v[162:165]
	v_mfma_f32_16x16x32_bf16 v[142:145], v[54:57], v[78:81], v[142:145]
	v_mfma_f32_16x16x32_bf16 v[138:141], v[62:65], v[78:81], v[138:141]
	v_mfma_f32_16x16x32_bf16 v[126:129], v[54:57], v[154:157], v[126:129]
	v_mfma_f32_16x16x32_bf16 v[122:125], v[62:65], v[154:157], v[122:125]
	v_mfma_f32_16x16x32_bf16 v[110:113], v[54:57], v[174:177], v[110:113]
	v_mfma_f32_16x16x32_bf16 v[106:109], v[62:65], v[174:177], v[106:109]
	s_barrier
	s_add_i32 s94, 0, 0x14000
	s_add_i32 s93, s93, s78
	v_add_u32_e32 v1, s94, v223
	v_lshl_add_u64 v[214:215], s[72:73], 0, v[202:203]
	s_mov_b32 m0, s93
	ds_read_b128 v[178:181], v1
	ds_read_b128 v[182:185], v1 offset:1024
	ds_read_b128 v[186:189], v1 offset:2048
	ds_read_b128 v[190:193], v1 offset:3072
	global_load_lds_dwordx4 v[214:215], off
	v_lshl_add_u64 v[236:237], s[72:73], 0, v[200:201]
	s_add_i32 m0, s93, 0x2000
	s_nop 0
	global_load_lds_dwordx4 v[236:237], off
	s_barrier
	s_waitcnt lgkmcnt(0)
	s_waitcnt lgkmcnt(0)
	v_mfma_f32_16x16x32_bf16 v[158:161], v[178:181], v[66:69], v[158:161]
	v_mfma_f32_16x16x32_bf16 v[66:69], v[186:189], v[66:69], v[150:153]
	v_mfma_f32_16x16x32_bf16 v[158:161], v[182:185], v[70:73], v[158:161]
	v_mfma_f32_16x16x32_bf16 v[66:69], v[190:193], v[70:73], v[66:69]
	v_mfma_f32_16x16x32_bf16 v[70:73], v[178:181], v[74:77], v[134:137]
	v_mfma_f32_16x16x32_bf16 v[74:77], v[186:189], v[74:77], v[130:133]
	v_mfma_f32_16x16x32_bf16 v[114:117], v[186:189], v[146:149], v[114:117]
	v_mfma_f32_16x16x32_bf16 v[102:105], v[178:181], v[170:173], v[102:105]
	v_mfma_f32_16x16x32_bf16 v[98:101], v[186:189], v[170:173], v[98:101]
	v_mfma_f32_16x16x32_bf16 v[70:73], v[182:185], v[78:81], v[70:73]
	v_mfma_f32_16x16x32_bf16 v[74:77], v[190:193], v[78:81], v[74:77]
	v_mfma_f32_16x16x32_bf16 v[78:81], v[178:181], v[146:149], v[118:121]
	v_mfma_f32_16x16x32_bf16 v[114:117], v[190:193], v[154:157], v[114:117]
	v_mfma_f32_16x16x32_bf16 v[102:105], v[182:185], v[174:177], v[102:105]
	v_mfma_f32_16x16x32_bf16 v[98:101], v[190:193], v[174:177], v[98:101]
	v_mfma_f32_16x16x32_bf16 v[78:81], v[182:185], v[154:157], v[78:81]
	s_mov_b32 m0, s79
	v_lshl_add_u64 v[238:239], s[42:43], 0, v[202:203]
	s_barrier
	ds_read_b128 v[118:121], v230 offset:16384
	ds_read_b128 v[130:133], v230 offset:17408
	ds_read_b128 v[134:137], v230 offset:18432
	ds_read_b128 v[146:149], v230 offset:19456
	ds_read_b128 v[150:153], v230 offset:20480
	ds_read_b128 v[154:157], v230 offset:21504
	ds_read_b128 v[170:173], v230 offset:22528
	ds_read_b128 v[174:177], v230 offset:23552
	global_load_lds_dwordx4 v[238:239], off
	v_lshl_add_u64 v[240:241], s[42:43], 0, v[200:201]
	s_mov_b32 m0, s80
	s_nop 0
	global_load_lds_dwordx4 v[240:241], off
	s_barrier
	s_waitcnt lgkmcnt(0)
	s_waitcnt lgkmcnt(0)
	v_mfma_f32_16x16x32_bf16 v[94:97], v[50:53], v[118:121], v[94:97]
	v_mfma_f32_16x16x32_bf16 v[90:93], v[58:61], v[118:121], v[90:93]
	v_mfma_f32_16x16x32_bf16 v[46:49], v[50:53], v[134:137], v[46:49]
	v_mfma_f32_16x16x32_bf16 v[42:45], v[58:61], v[134:137], v[42:45]
	v_mfma_f32_16x16x32_bf16 v[30:33], v[50:53], v[150:153], v[30:33]
	v_mfma_f32_16x16x32_bf16 v[26:29], v[58:61], v[150:153], v[26:29]
	v_mfma_f32_16x16x32_bf16 v[14:17], v[50:53], v[170:173], v[14:17]
	v_mfma_f32_16x16x32_bf16 v[10:13], v[58:61], v[170:173], v[10:13]
	v_mfma_f32_16x16x32_bf16 v[94:97], v[54:57], v[130:133], v[94:97]
	v_mfma_f32_16x16x32_bf16 v[90:93], v[62:65], v[130:133], v[90:93]
	v_mfma_f32_16x16x32_bf16 v[46:49], v[54:57], v[146:149], v[46:49]
	v_mfma_f32_16x16x32_bf16 v[42:45], v[62:65], v[146:149], v[42:45]
	v_mfma_f32_16x16x32_bf16 v[30:33], v[54:57], v[154:157], v[30:33]
	v_mfma_f32_16x16x32_bf16 v[26:29], v[62:65], v[154:157], v[26:29]
	v_mfma_f32_16x16x32_bf16 v[14:17], v[54:57], v[174:177], v[14:17]
	v_mfma_f32_16x16x32_bf16 v[10:13], v[62:65], v[174:177], v[10:13]
	s_barrier
	s_add_u32 s72, s72, s4
	s_addc_u32 s73, s73, 0
	s_add_i32 s93, s94, s78
	v_lshl_add_u64 v[242:243], s[72:73], 0, v[202:203]
	s_mov_b32 m0, s93
	v_lshl_add_u64 v[244:245], s[72:73], 0, v[200:201]
	global_load_lds_dwordx4 v[242:243], off
	s_add_i32 m0, s93, 0x2000
	s_nop 0
	global_load_lds_dwordx4 v[244:245], off
	s_waitcnt vmcnt(6)
	s_barrier
	v_mfma_f32_16x16x32_bf16 v[38:41], v[178:181], v[134:137], v[38:41]
	v_mfma_f32_16x16x32_bf16 v[34:37], v[186:189], v[134:137], v[34:37]
	v_mfma_f32_16x16x32_bf16 v[22:25], v[178:181], v[150:153], v[22:25]
	v_mfma_f32_16x16x32_bf16 v[18:21], v[186:189], v[150:153], v[18:21]
	v_mfma_f32_16x16x32_bf16 v[6:9], v[178:181], v[170:173], v[6:9]
	v_mfma_f32_16x16x32_bf16 v[2:5], v[186:189], v[170:173], v[2:5]
	v_mfma_f32_16x16x32_bf16 v[50:53], v[178:181], v[118:121], v[86:89]
	v_mfma_f32_16x16x32_bf16 v[54:57], v[186:189], v[118:121], v[82:85]
	v_mfma_f32_16x16x32_bf16 v[38:41], v[182:185], v[146:149], v[38:41]
	v_mfma_f32_16x16x32_bf16 v[34:37], v[190:193], v[146:149], v[34:37]
	v_mfma_f32_16x16x32_bf16 v[22:25], v[182:185], v[154:157], v[22:25]
	v_mfma_f32_16x16x32_bf16 v[18:21], v[190:193], v[154:157], v[18:21]
	v_mfma_f32_16x16x32_bf16 v[6:9], v[182:185], v[174:177], v[6:9]
	v_mfma_f32_16x16x32_bf16 v[2:5], v[190:193], v[174:177], v[2:5]
	v_mfma_f32_16x16x32_bf16 v[50:53], v[182:185], v[130:133], v[50:53]
	v_mfma_f32_16x16x32_bf16 v[54:57], v[190:193], v[130:133], v[54:57]
	s_add_i32 s72, 0, 0x18000
	v_add_u32_e32 v1, s72, v223
	s_barrier
	ds_read_b128 v[58:61], v1
	ds_read_b128 v[62:65], v1 offset:1024
	ds_read_b128 v[82:85], v1 offset:2048
	ds_read_b128 v[86:89], v1 offset:3072
	s_add_u32 s42, s42, s4
	s_addc_u32 s43, s43, 0
	s_mov_b32 m0, s81
	v_lshl_add_u64 v[134:135], s[42:43], 0, v[202:203]
	ds_read_b128 v[118:121], v230 offset:32768
	ds_read_b128 v[130:133], v230 offset:33792
	ds_read_b128 v[146:149], v230 offset:34816
	ds_read_b128 v[154:157], v230 offset:35840
	ds_read_b128 v[170:173], v230 offset:36864
	ds_read_b128 v[174:177], v230 offset:37888
	ds_read_b128 v[178:181], v230 offset:38912
	ds_read_b128 v[182:185], v230 offset:39936
	global_load_lds_dwordx4 v[134:135], off
	v_lshl_add_u64 v[134:135], s[42:43], 0, v[200:201]
	s_mov_b32 m0, s82
	s_nop 0
	global_load_lds_dwordx4 v[134:135], off
	s_waitcnt lgkmcnt(8)
	s_barrier
	s_waitcnt lgkmcnt(0)
	s_waitcnt lgkmcnt(0)
	v_mfma_f32_16x16x32_bf16 v[134:137], v[58:61], v[118:121], v[166:169]
	v_mfma_f32_16x16x32_bf16 v[166:169], v[62:65], v[130:133], v[134:137]
	v_mfma_f32_16x16x32_bf16 v[134:137], v[82:85], v[118:121], v[162:165]
	v_mfma_f32_16x16x32_bf16 v[162:165], v[86:89], v[130:133], v[134:137]
	v_mfma_f32_16x16x32_bf16 v[134:137], v[58:61], v[146:149], v[142:145]
	v_mfma_f32_16x16x32_bf16 v[142:145], v[62:65], v[154:157], v[134:137]
	v_mfma_f32_16x16x32_bf16 v[134:137], v[82:85], v[146:149], v[138:141]
	v_mfma_f32_16x16x32_bf16 v[126:129], v[58:61], v[170:173], v[126:129]
	v_mfma_f32_16x16x32_bf16 v[122:125], v[82:85], v[170:173], v[122:125]
	v_mfma_f32_16x16x32_bf16 v[110:113], v[58:61], v[178:181], v[110:113]
	v_mfma_f32_16x16x32_bf16 v[106:109], v[82:85], v[178:181], v[106:109]
	v_mfma_f32_16x16x32_bf16 v[138:141], v[86:89], v[154:157], v[134:137]
	v_mfma_f32_16x16x32_bf16 v[126:129], v[62:65], v[174:177], v[126:129]
	v_mfma_f32_16x16x32_bf16 v[122:125], v[86:89], v[174:177], v[122:125]
	v_mfma_f32_16x16x32_bf16 v[110:113], v[62:65], v[182:185], v[110:113]
	v_mfma_f32_16x16x32_bf16 v[106:109], v[86:89], v[182:185], v[106:109]
	s_barrier
	s_add_i32 s42, 0, 0x1c000
	s_add_i32 s43, s72, s78
	v_add_u32_e32 v1, s42, v223
	v_lshl_add_u64 v[134:135], v[214:215], 0, s[22:23]
	s_mov_b32 m0, s43
	ds_read_b128 v[186:189], v1
	ds_read_b128 v[190:193], v1 offset:1024
	ds_read_b128 v[208:211], v1 offset:2048
	ds_read_b128 v[232:235], v1 offset:3072
	global_load_lds_dwordx4 v[134:135], off
	v_lshl_add_u64 v[134:135], v[236:237], 0, s[22:23]
	s_add_i32 m0, s43, 0x2000
	s_nop 0
	global_load_lds_dwordx4 v[134:135], off
	s_barrier
	s_waitcnt lgkmcnt(0)
	s_waitcnt lgkmcnt(0)
	v_mfma_f32_16x16x32_bf16 v[66:69], v[208:211], v[118:121], v[66:69]
	v_mfma_f32_16x16x32_bf16 v[134:137], v[186:189], v[118:121], v[158:161]
	v_mfma_f32_16x16x32_bf16 v[150:153], v[232:235], v[130:133], v[66:69]
	v_mfma_f32_16x16x32_bf16 v[66:69], v[186:189], v[146:149], v[70:73]
	v_mfma_f32_16x16x32_bf16 v[158:161], v[190:193], v[130:133], v[134:137]
	v_mfma_f32_16x16x32_bf16 v[134:137], v[190:193], v[154:157], v[66:69]
	v_mfma_f32_16x16x32_bf16 v[66:69], v[208:211], v[146:149], v[74:77]
	v_mfma_f32_16x16x32_bf16 v[130:133], v[232:235], v[154:157], v[66:69]
	v_mfma_f32_16x16x32_bf16 v[66:69], v[186:189], v[170:173], v[78:81]
	v_mfma_f32_16x16x32_bf16 v[118:121], v[190:193], v[174:177], v[66:69]
	v_mfma_f32_16x16x32_bf16 v[66:69], v[208:211], v[170:173], v[114:117]
	v_mfma_f32_16x16x32_bf16 v[114:117], v[232:235], v[174:177], v[66:69]
	v_mfma_f32_16x16x32_bf16 v[66:69], v[186:189], v[178:181], v[102:105]
	v_mfma_f32_16x16x32_bf16 v[102:105], v[190:193], v[182:185], v[66:69]
	v_mfma_f32_16x16x32_bf16 v[66:69], v[208:211], v[178:181], v[98:101]
	v_mfma_f32_16x16x32_bf16 v[98:101], v[232:235], v[182:185], v[66:69]
	s_mov_b32 m0, s86
	v_lshl_add_u64 v[178:179], v[238:239], 0, s[22:23]
	s_barrier
	s_nop 2
	ds_read_b128 v[66:69], v230 offset:49152
	ds_read_b128 v[70:73], v230 offset:50176
	ds_read_b128 v[74:77], v230 offset:51200
	ds_read_b128 v[78:81], v230 offset:52224
	ds_read_b128 v[146:149], v230 offset:53248
	ds_read_b128 v[154:157], v230 offset:54272
	ds_read_b128 v[170:173], v230 offset:55296
	ds_read_b128 v[174:177], v230 offset:56320
	global_load_lds_dwordx4 v[178:179], off
	v_lshl_add_u64 v[178:179], v[240:241], 0, s[22:23]
	s_mov_b32 m0, s87
	s_nop 0
	global_load_lds_dwordx4 v[178:179], off
	s_barrier
	s_waitcnt lgkmcnt(0)
	s_waitcnt lgkmcnt(0)
	v_mfma_f32_16x16x32_bf16 v[94:97], v[58:61], v[66:69], v[94:97]
	v_mfma_f32_16x16x32_bf16 v[90:93], v[82:85], v[66:69], v[90:93]
	v_mfma_f32_16x16x32_bf16 v[46:49], v[58:61], v[74:77], v[46:49]
	v_mfma_f32_16x16x32_bf16 v[42:45], v[82:85], v[74:77], v[42:45]
	v_mfma_f32_16x16x32_bf16 v[30:33], v[58:61], v[146:149], v[30:33]
	v_mfma_f32_16x16x32_bf16 v[26:29], v[82:85], v[146:149], v[26:29]
	v_mfma_f32_16x16x32_bf16 v[14:17], v[58:61], v[170:173], v[14:17]
	v_mfma_f32_16x16x32_bf16 v[10:13], v[82:85], v[170:173], v[10:13]
	v_mfma_f32_16x16x32_bf16 v[94:97], v[62:65], v[70:73], v[94:97]
	v_mfma_f32_16x16x32_bf16 v[90:93], v[86:89], v[70:73], v[90:93]
	v_mfma_f32_16x16x32_bf16 v[46:49], v[62:65], v[78:81], v[46:49]
	v_mfma_f32_16x16x32_bf16 v[42:45], v[86:89], v[78:81], v[42:45]
	v_mfma_f32_16x16x32_bf16 v[30:33], v[62:65], v[154:157], v[30:33]
	v_mfma_f32_16x16x32_bf16 v[26:29], v[86:89], v[154:157], v[26:29]
	v_mfma_f32_16x16x32_bf16 v[14:17], v[62:65], v[174:177], v[14:17]
	v_mfma_f32_16x16x32_bf16 v[10:13], v[86:89], v[174:177], v[10:13]
	s_barrier
	s_add_i32 s42, s42, s78
	v_lshl_add_u64 v[58:59], v[242:243], 0, s[22:23]
	s_mov_b32 m0, s42
	s_nop 0
	global_load_lds_dwordx4 v[58:59], off
	v_lshl_add_u64 v[58:59], v[244:245], 0, s[22:23]
	s_add_i32 m0, s42, 0x2000
	s_nop 0
	global_load_lds_dwordx4 v[58:59], off
	s_waitcnt vmcnt(6)
	s_barrier
	v_mfma_f32_16x16x32_bf16 v[50:53], v[186:189], v[66:69], v[50:53]
	v_mfma_f32_16x16x32_bf16 v[86:89], v[190:193], v[70:73], v[50:53]
	v_mfma_f32_16x16x32_bf16 v[50:53], v[208:211], v[66:69], v[54:57]
	v_mfma_f32_16x16x32_bf16 v[38:41], v[186:189], v[74:77], v[38:41]
	v_mfma_f32_16x16x32_bf16 v[34:37], v[208:211], v[74:77], v[34:37]
	v_mfma_f32_16x16x32_bf16 v[22:25], v[186:189], v[146:149], v[22:25]
	v_mfma_f32_16x16x32_bf16 v[18:21], v[208:211], v[146:149], v[18:21]
	v_mfma_f32_16x16x32_bf16 v[6:9], v[186:189], v[170:173], v[6:9]
	v_mfma_f32_16x16x32_bf16 v[2:5], v[208:211], v[170:173], v[2:5]
	v_mfma_f32_16x16x32_bf16 v[82:85], v[232:235], v[70:73], v[50:53]
	v_mfma_f32_16x16x32_bf16 v[38:41], v[190:193], v[78:81], v[38:41]
	v_mfma_f32_16x16x32_bf16 v[34:37], v[232:235], v[78:81], v[34:37]
	v_mfma_f32_16x16x32_bf16 v[22:25], v[190:193], v[154:157], v[22:25]
	v_mfma_f32_16x16x32_bf16 v[18:21], v[232:235], v[154:157], v[18:21]
	v_mfma_f32_16x16x32_bf16 v[6:9], v[190:193], v[174:177], v[6:9]
	v_mfma_f32_16x16x32_bf16 v[2:5], v[232:235], v[174:177], v[2:5]
	s_add_u32 s27, s27, 0x100
	s_addc_u32 s91, s91, 0
	s_add_u32 s36, s36, 0x100
	s_addc_u32 s37, s37, 0
	s_cmp_ge_u32 s92, s32
	s_mov_b32 s42, s92
	s_barrier
	s_cbranch_scc0 .LBB0_1179
	s_cmp_eq_u32 s32, s84
	s_cbranch_scc1 .Ltail_done_1
	s_lshl_b32 s32, s3, 8
	s_add_i32 s32, s32, s85
	v_or_b32_e32 v249, s32, v221
	v_lshlrev_b32_e32 v249, 11, v249
	v_lshl_or_b32 v248, s38, 8, v224
	v_lshl_add_u32 v249, v248, 1, v249
	s_add_i32 s92, s42, 2
	s_add_u32 s72, s36, 0x80
	s_addc_u32 s43, s37, 0
	s_add_i32 s93, 0, 0x10000
	v_add_u32_e32 v1, s93, v223
	ds_read_b128 v[50:53], v1
	ds_read_b128 v[54:57], v1 offset:1024
	ds_read_b128 v[58:61], v1 offset:2048
	ds_read_b128 v[62:65], v1 offset:3072
	s_cmp_eq_u32 s88, s42
	s_cselect_b32 s42, s66, s72
	s_cselect_b32 s43, s67, s43
	s_cselect_b32 s73, s71, s91
	s_cselect_b32 s72, s70, s27
	v_lshl_add_u64 v[178:179], s[36:37], 0, v[206:207]
	s_add_i32 m0, s79, 0xc000
	ds_read_b128 v[66:69], v230
	ds_read_b128 v[70:73], v230 offset:1024
	ds_read_b128 v[74:77], v230 offset:2048
	ds_read_b128 v[78:81], v230 offset:3072
	ds_read_b128 v[146:149], v230 offset:4096
	ds_read_b128 v[154:157], v230 offset:5120
	ds_read_b128 v[170:173], v230 offset:6144
	ds_read_b128 v[174:177], v230 offset:7168
	global_load_lds_dwordx4 v[178:179], off
	v_lshl_add_u64 v[178:179], s[36:37], 0, v[204:205]
	s_add_i32 m0, s79, 0xe000
	s_nop 0
	global_load_lds_dwordx4 v[178:179], off
	s_waitcnt lgkmcnt(8)
	s_barrier
	s_waitcnt lgkmcnt(0)
	s_waitcnt lgkmcnt(0)
	v_mfma_f32_16x16x32_bf16 v[166:169], v[50:53], v[66:69], v[166:169]
	v_mfma_f32_16x16x32_bf16 v[162:165], v[58:61], v[66:69], v[162:165]
	v_mfma_f32_16x16x32_bf16 v[142:145], v[50:53], v[74:77], v[142:145]
	v_mfma_f32_16x16x32_bf16 v[138:141], v[58:61], v[74:77], v[138:141]
	v_mfma_f32_16x16x32_bf16 v[126:129], v[50:53], v[146:149], v[126:129]
	v_mfma_f32_16x16x32_bf16 v[122:125], v[58:61], v[146:149], v[122:125]
	v_mfma_f32_16x16x32_bf16 v[110:113], v[50:53], v[170:173], v[110:113]
	v_mfma_f32_16x16x32_bf16 v[106:109], v[58:61], v[170:173], v[106:109]
	v_mfma_f32_16x16x32_bf16 v[166:169], v[54:57], v[70:73], v[166:169]
	v_mfma_f32_16x16x32_bf16 v[162:165], v[62:65], v[70:73], v[162:165]
	v_mfma_f32_16x16x32_bf16 v[142:145], v[54:57], v[78:81], v[142:145]
	v_mfma_f32_16x16x32_bf16 v[138:141], v[62:65], v[78:81], v[138:141]
	v_mfma_f32_16x16x32_bf16 v[126:129], v[54:57], v[154:157], v[126:129]
	v_mfma_f32_16x16x32_bf16 v[122:125], v[62:65], v[154:157], v[122:125]
	v_mfma_f32_16x16x32_bf16 v[110:113], v[54:57], v[174:177], v[110:113]
	v_mfma_f32_16x16x32_bf16 v[106:109], v[62:65], v[174:177], v[106:109]
	s_barrier
	s_add_i32 s94, 0, 0x14000
	s_add_i32 s93, s93, s78
	v_add_u32_e32 v1, s94, v223
	v_lshl_add_u64 v[214:215], s[72:73], 0, v[202:203]
	s_mov_b32 m0, s93
	ds_read_b128 v[178:181], v1
	ds_read_b128 v[182:185], v1 offset:1024
	ds_read_b128 v[186:189], v1 offset:2048
	ds_read_b128 v[190:193], v1 offset:3072
	v_lshl_add_u64 v[236:237], s[72:73], 0, v[200:201]
	s_add_i32 m0, s93, 0x2000
	s_nop 0
	v_mov_b32_e32 v250, v249
	global_load_dword v251, v250, s[48:49]
	global_load_dword v251, v250, s[48:49] offset:256
	v_add_u32_e32 v250, 0x8000, v249
	global_load_dword v251, v250, s[48:49]
	global_load_dword v251, v250, s[48:49] offset:256
	v_add_u32_e32 v250, 0x10000, v249
	global_load_dword v251, v250, s[48:49]
	global_load_dword v251, v250, s[48:49] offset:256
	v_add_u32_e32 v250, 0x18000, v249
	global_load_dword v251, v250, s[48:49]
	global_load_dword v251, v250, s[48:49] offset:256
	v_add_u32_e32 v250, 0x40000, v249
	global_load_dword v251, v250, s[48:49]
	global_load_dword v251, v250, s[48:49] offset:256
	v_add_u32_e32 v250, 0x48000, v249
	global_load_dword v251, v250, s[48:49]
	global_load_dword v251, v250, s[48:49] offset:256
	v_add_u32_e32 v250, 0x50000, v249
	global_load_dword v251, v250, s[48:49]
	global_load_dword v251, v250, s[48:49] offset:256
	v_add_u32_e32 v250, 0x58000, v249
	global_load_dword v251, v250, s[48:49]
	global_load_dword v251, v250, s[48:49] offset:256
	s_barrier
	s_waitcnt lgkmcnt(0)
	s_waitcnt lgkmcnt(0)
	v_mfma_f32_16x16x32_bf16 v[158:161], v[178:181], v[66:69], v[158:161]
	v_mfma_f32_16x16x32_bf16 v[66:69], v[186:189], v[66:69], v[150:153]
	v_mfma_f32_16x16x32_bf16 v[158:161], v[182:185], v[70:73], v[158:161]
	v_mfma_f32_16x16x32_bf16 v[66:69], v[190:193], v[70:73], v[66:69]
	v_mfma_f32_16x16x32_bf16 v[70:73], v[178:181], v[74:77], v[134:137]
	v_mfma_f32_16x16x32_bf16 v[74:77], v[186:189], v[74:77], v[130:133]
	v_mfma_f32_16x16x32_bf16 v[114:117], v[186:189], v[146:149], v[114:117]
	v_mfma_f32_16x16x32_bf16 v[102:105], v[178:181], v[170:173], v[102:105]
	v_mfma_f32_16x16x32_bf16 v[98:101], v[186:189], v[170:173], v[98:101]
	v_mfma_f32_16x16x32_bf16 v[70:73], v[182:185], v[78:81], v[70:73]
	v_mfma_f32_16x16x32_bf16 v[74:77], v[190:193], v[78:81], v[74:77]
	v_mfma_f32_16x16x32_bf16 v[78:81], v[178:181], v[146:149], v[118:121]
	v_mfma_f32_16x16x32_bf16 v[114:117], v[190:193], v[154:157], v[114:117]
	v_mfma_f32_16x16x32_bf16 v[102:105], v[182:185], v[174:177], v[102:105]
	v_mfma_f32_16x16x32_bf16 v[98:101], v[190:193], v[174:177], v[98:101]
	v_mfma_f32_16x16x32_bf16 v[78:81], v[182:185], v[154:157], v[78:81]
	s_mov_b32 m0, s79
	v_lshl_add_u64 v[238:239], s[42:43], 0, v[202:203]
	s_barrier
	ds_read_b128 v[118:121], v230 offset:16384
	ds_read_b128 v[130:133], v230 offset:17408
	ds_read_b128 v[134:137], v230 offset:18432
	ds_read_b128 v[146:149], v230 offset:19456
	ds_read_b128 v[150:153], v230 offset:20480
	ds_read_b128 v[154:157], v230 offset:21504
	ds_read_b128 v[170:173], v230 offset:22528
	ds_read_b128 v[174:177], v230 offset:23552
	v_lshl_add_u64 v[240:241], s[42:43], 0, v[200:201]
	s_mov_b32 m0, s80
	s_nop 0
	s_barrier
	s_waitcnt lgkmcnt(0)
	s_waitcnt lgkmcnt(0)
	v_mfma_f32_16x16x32_bf16 v[94:97], v[50:53], v[118:121], v[94:97]
	v_mfma_f32_16x16x32_bf16 v[90:93], v[58:61], v[118:121], v[90:93]
	v_mfma_f32_16x16x32_bf16 v[46:49], v[50:53], v[134:137], v[46:49]
	v_mfma_f32_16x16x32_bf16 v[42:45], v[58:61], v[134:137], v[42:45]
	v_mfma_f32_16x16x32_bf16 v[30:33], v[50:53], v[150:153], v[30:33]
	v_mfma_f32_16x16x32_bf16 v[26:29], v[58:61], v[150:153], v[26:29]
	v_mfma_f32_16x16x32_bf16 v[14:17], v[50:53], v[170:173], v[14:17]
	v_mfma_f32_16x16x32_bf16 v[10:13], v[58:61], v[170:173], v[10:13]
	v_mfma_f32_16x16x32_bf16 v[94:97], v[54:57], v[130:133], v[94:97]
	v_mfma_f32_16x16x32_bf16 v[90:93], v[62:65], v[130:133], v[90:93]
	v_mfma_f32_16x16x32_bf16 v[46:49], v[54:57], v[146:149], v[46:49]
	v_mfma_f32_16x16x32_bf16 v[42:45], v[62:65], v[146:149], v[42:45]
	v_mfma_f32_16x16x32_bf16 v[30:33], v[54:57], v[154:157], v[30:33]
	v_mfma_f32_16x16x32_bf16 v[26:29], v[62:65], v[154:157], v[26:29]
	v_mfma_f32_16x16x32_bf16 v[14:17], v[54:57], v[174:177], v[14:17]
	v_mfma_f32_16x16x32_bf16 v[10:13], v[62:65], v[174:177], v[10:13]
	s_barrier
	s_add_u32 s72, s72, s4
	s_addc_u32 s73, s73, 0
	s_add_i32 s93, s94, s78
	v_lshl_add_u64 v[242:243], s[72:73], 0, v[202:203]
	s_mov_b32 m0, s93
	v_lshl_add_u64 v[244:245], s[72:73], 0, v[200:201]
	s_add_i32 m0, s93, 0x2000
	s_nop 0
	s_waitcnt vmcnt(16)
	s_barrier
	v_mfma_f32_16x16x32_bf16 v[38:41], v[178:181], v[134:137], v[38:41]
	v_mfma_f32_16x16x32_bf16 v[34:37], v[186:189], v[134:137], v[34:37]
	v_mfma_f32_16x16x32_bf16 v[22:25], v[178:181], v[150:153], v[22:25]
	v_mfma_f32_16x16x32_bf16 v[18:21], v[186:189], v[150:153], v[18:21]
	v_mfma_f32_16x16x32_bf16 v[6:9], v[178:181], v[170:173], v[6:9]
	v_mfma_f32_16x16x32_bf16 v[2:5], v[186:189], v[170:173], v[2:5]
	v_mfma_f32_16x16x32_bf16 v[50:53], v[178:181], v[118:121], v[86:89]
	v_mfma_f32_16x16x32_bf16 v[54:57], v[186:189], v[118:121], v[82:85]
	v_mfma_f32_16x16x32_bf16 v[38:41], v[182:185], v[146:149], v[38:41]
	v_mfma_f32_16x16x32_bf16 v[34:37], v[190:193], v[146:149], v[34:37]
	v_mfma_f32_16x16x32_bf16 v[22:25], v[182:185], v[154:157], v[22:25]
	v_mfma_f32_16x16x32_bf16 v[18:21], v[190:193], v[154:157], v[18:21]
	v_mfma_f32_16x16x32_bf16 v[6:9], v[182:185], v[174:177], v[6:9]
	v_mfma_f32_16x16x32_bf16 v[2:5], v[190:193], v[174:177], v[2:5]
	v_mfma_f32_16x16x32_bf16 v[50:53], v[182:185], v[130:133], v[50:53]
	v_mfma_f32_16x16x32_bf16 v[54:57], v[190:193], v[130:133], v[54:57]
	s_add_i32 s72, 0, 0x18000
	v_add_u32_e32 v1, s72, v223
	s_barrier
	ds_read_b128 v[58:61], v1
	ds_read_b128 v[62:65], v1 offset:1024
	ds_read_b128 v[82:85], v1 offset:2048
	ds_read_b128 v[86:89], v1 offset:3072
	s_add_u32 s42, s42, s4
	s_addc_u32 s43, s43, 0
	s_mov_b32 m0, s81
	v_lshl_add_u64 v[134:135], s[42:43], 0, v[202:203]
	ds_read_b128 v[118:121], v230 offset:32768
	ds_read_b128 v[130:133], v230 offset:33792
	ds_read_b128 v[146:149], v230 offset:34816
	ds_read_b128 v[154:157], v230 offset:35840
	ds_read_b128 v[170:173], v230 offset:36864
	ds_read_b128 v[174:177], v230 offset:37888
	ds_read_b128 v[178:181], v230 offset:38912
	ds_read_b128 v[182:185], v230 offset:39936
	v_lshl_add_u64 v[134:135], s[42:43], 0, v[200:201]
	s_mov_b32 m0, s82
	s_nop 0
	s_waitcnt lgkmcnt(8)
	s_barrier
	s_waitcnt lgkmcnt(0)
	s_waitcnt lgkmcnt(0)
	v_mfma_f32_16x16x32_bf16 v[134:137], v[58:61], v[118:121], v[166:169]
	v_mfma_f32_16x16x32_bf16 v[166:169], v[62:65], v[130:133], v[134:137]
	v_mfma_f32_16x16x32_bf16 v[134:137], v[82:85], v[118:121], v[162:165]
	v_mfma_f32_16x16x32_bf16 v[162:165], v[86:89], v[130:133], v[134:137]
	v_mfma_f32_16x16x32_bf16 v[134:137], v[58:61], v[146:149], v[142:145]
	v_mfma_f32_16x16x32_bf16 v[142:145], v[62:65], v[154:157], v[134:137]
	v_mfma_f32_16x16x32_bf16 v[134:137], v[82:85], v[146:149], v[138:141]
	v_mfma_f32_16x16x32_bf16 v[126:129], v[58:61], v[170:173], v[126:129]
	v_mfma_f32_16x16x32_bf16 v[122:125], v[82:85], v[170:173], v[122:125]
	v_mfma_f32_16x16x32_bf16 v[110:113], v[58:61], v[178:181], v[110:113]
	v_mfma_f32_16x16x32_bf16 v[106:109], v[82:85], v[178:181], v[106:109]
	v_mfma_f32_16x16x32_bf16 v[138:141], v[86:89], v[154:157], v[134:137]
	v_mfma_f32_16x16x32_bf16 v[126:129], v[62:65], v[174:177], v[126:129]
	v_mfma_f32_16x16x32_bf16 v[122:125], v[86:89], v[174:177], v[122:125]
	v_mfma_f32_16x16x32_bf16 v[110:113], v[62:65], v[182:185], v[110:113]
	v_mfma_f32_16x16x32_bf16 v[106:109], v[86:89], v[182:185], v[106:109]
	s_barrier
	s_add_i32 s42, 0, 0x1c000
	s_add_i32 s43, s72, s78
	v_add_u32_e32 v1, s42, v223
	v_lshl_add_u64 v[134:135], v[214:215], 0, s[22:23]
	s_mov_b32 m0, s43
	ds_read_b128 v[186:189], v1
	ds_read_b128 v[190:193], v1 offset:1024
	ds_read_b128 v[208:211], v1 offset:2048
	ds_read_b128 v[232:235], v1 offset:3072
	v_lshl_add_u64 v[134:135], v[236:237], 0, s[22:23]
	s_add_i32 m0, s43, 0x2000
	s_nop 0
	s_barrier
	s_waitcnt lgkmcnt(0)
	s_waitcnt lgkmcnt(0)
	v_mfma_f32_16x16x32_bf16 v[66:69], v[208:211], v[118:121], v[66:69]
	v_mfma_f32_16x16x32_bf16 v[134:137], v[186:189], v[118:121], v[158:161]
	v_mfma_f32_16x16x32_bf16 v[150:153], v[232:235], v[130:133], v[66:69]
	v_mfma_f32_16x16x32_bf16 v[66:69], v[186:189], v[146:149], v[70:73]
	v_mfma_f32_16x16x32_bf16 v[158:161], v[190:193], v[130:133], v[134:137]
	v_mfma_f32_16x16x32_bf16 v[134:137], v[190:193], v[154:157], v[66:69]
	v_mfma_f32_16x16x32_bf16 v[66:69], v[208:211], v[146:149], v[74:77]
	v_mfma_f32_16x16x32_bf16 v[130:133], v[232:235], v[154:157], v[66:69]
	v_mfma_f32_16x16x32_bf16 v[66:69], v[186:189], v[170:173], v[78:81]
	v_mfma_f32_16x16x32_bf16 v[118:121], v[190:193], v[174:177], v[66:69]
	v_mfma_f32_16x16x32_bf16 v[66:69], v[208:211], v[170:173], v[114:117]
	v_mfma_f32_16x16x32_bf16 v[114:117], v[232:235], v[174:177], v[66:69]
	v_mfma_f32_16x16x32_bf16 v[66:69], v[186:189], v[178:181], v[102:105]
	v_mfma_f32_16x16x32_bf16 v[102:105], v[190:193], v[182:185], v[66:69]
	v_mfma_f32_16x16x32_bf16 v[66:69], v[208:211], v[178:181], v[98:101]
	v_mfma_f32_16x16x32_bf16 v[98:101], v[232:235], v[182:185], v[66:69]
	s_mov_b32 m0, s86
	v_lshl_add_u64 v[178:179], v[238:239], 0, s[22:23]
	s_barrier
	s_nop 2
	ds_read_b128 v[66:69], v230 offset:49152
	ds_read_b128 v[70:73], v230 offset:50176
	ds_read_b128 v[74:77], v230 offset:51200
	ds_read_b128 v[78:81], v230 offset:52224
	ds_read_b128 v[146:149], v230 offset:53248
	ds_read_b128 v[154:157], v230 offset:54272
	ds_read_b128 v[170:173], v230 offset:55296
	ds_read_b128 v[174:177], v230 offset:56320
	v_lshl_add_u64 v[178:179], v[240:241], 0, s[22:23]
	s_mov_b32 m0, s87
	s_nop 0
	s_barrier
	s_waitcnt lgkmcnt(0)
	s_waitcnt lgkmcnt(0)
	v_mfma_f32_16x16x32_bf16 v[94:97], v[58:61], v[66:69], v[94:97]
	v_mfma_f32_16x16x32_bf16 v[90:93], v[82:85], v[66:69], v[90:93]
	v_mfma_f32_16x16x32_bf16 v[46:49], v[58:61], v[74:77], v[46:49]
	v_mfma_f32_16x16x32_bf16 v[42:45], v[82:85], v[74:77], v[42:45]
	v_mfma_f32_16x16x32_bf16 v[30:33], v[58:61], v[146:149], v[30:33]
	v_mfma_f32_16x16x32_bf16 v[26:29], v[82:85], v[146:149], v[26:29]
	v_mfma_f32_16x16x32_bf16 v[14:17], v[58:61], v[170:173], v[14:17]
	v_mfma_f32_16x16x32_bf16 v[10:13], v[82:85], v[170:173], v[10:13]
	v_mfma_f32_16x16x32_bf16 v[94:97], v[62:65], v[70:73], v[94:97]
	v_mfma_f32_16x16x32_bf16 v[90:93], v[86:89], v[70:73], v[90:93]
	v_mfma_f32_16x16x32_bf16 v[46:49], v[62:65], v[78:81], v[46:49]
	v_mfma_f32_16x16x32_bf16 v[42:45], v[86:89], v[78:81], v[42:45]
	v_mfma_f32_16x16x32_bf16 v[30:33], v[62:65], v[154:157], v[30:33]
	v_mfma_f32_16x16x32_bf16 v[26:29], v[86:89], v[154:157], v[26:29]
	v_mfma_f32_16x16x32_bf16 v[14:17], v[62:65], v[174:177], v[14:17]
	v_mfma_f32_16x16x32_bf16 v[10:13], v[86:89], v[174:177], v[10:13]
	s_barrier
	s_add_i32 s42, s42, s78
	v_lshl_add_u64 v[58:59], v[242:243], 0, s[22:23]
	s_mov_b32 m0, s42
	s_nop 0
	v_lshl_add_u64 v[58:59], v[244:245], 0, s[22:23]
	s_add_i32 m0, s42, 0x2000
	s_nop 0
	s_barrier
	v_mfma_f32_16x16x32_bf16 v[50:53], v[186:189], v[66:69], v[50:53]
	v_mfma_f32_16x16x32_bf16 v[86:89], v[190:193], v[70:73], v[50:53]
	v_mfma_f32_16x16x32_bf16 v[50:53], v[208:211], v[66:69], v[54:57]
	v_mfma_f32_16x16x32_bf16 v[38:41], v[186:189], v[74:77], v[38:41]
	v_mfma_f32_16x16x32_bf16 v[34:37], v[208:211], v[74:77], v[34:37]
	v_mfma_f32_16x16x32_bf16 v[22:25], v[186:189], v[146:149], v[22:25]
	v_mfma_f32_16x16x32_bf16 v[18:21], v[208:211], v[146:149], v[18:21]
	v_mfma_f32_16x16x32_bf16 v[6:9], v[186:189], v[170:173], v[6:9]
	v_mfma_f32_16x16x32_bf16 v[2:5], v[208:211], v[170:173], v[2:5]
	v_mfma_f32_16x16x32_bf16 v[82:85], v[232:235], v[70:73], v[50:53]
	v_mfma_f32_16x16x32_bf16 v[38:41], v[190:193], v[78:81], v[38:41]
	v_mfma_f32_16x16x32_bf16 v[34:37], v[232:235], v[78:81], v[34:37]
	v_mfma_f32_16x16x32_bf16 v[22:25], v[190:193], v[154:157], v[22:25]
	v_mfma_f32_16x16x32_bf16 v[18:21], v[232:235], v[154:157], v[18:21]
	v_mfma_f32_16x16x32_bf16 v[6:9], v[190:193], v[174:177], v[6:9]
	v_mfma_f32_16x16x32_bf16 v[2:5], v[232:235], v[174:177], v[2:5]
	s_add_u32 s27, s27, 0x100
	s_addc_u32 s91, s91, 0
	s_add_u32 s36, s36, 0x100
	s_addc_u32 s37, s37, 0
	s_cmp_ge_u32 s92, s84
	s_mov_b32 s42, s92
	s_barrier
